# P0 de-serialisation: phase-0 rowconv and weight-tile conversions issue all 4 loads up front with counted vmcnt (was load-wait-store ladder), on top of v052
# speedup vs baseline: 1.0275x; 1.0221x over previous
.LBB0_287:
	s_cmpk_gt_i32 s2, 0x181f
	s_mov_b64 s[22:23], -1
	s_cbranch_scc0 .LBB0_297
	s_cmpk_gt_u32 s2, 0x201f
	s_cbranch_scc0 .LBB0_292
	v_ashrrev_i32_e32 v21, 31, v20
	s_waitcnt lgkmcnt(0)
	v_lshlrev_b64 v[2:3], 12, v[20:21]
	v_lshl_add_u64 v[30:31], v[12:13], 0, v[2:3]
	v_lshlrev_b64 v[6:7], 11, v[20:21]
	v_lshl_add_u64 v[34:35], v[18:19], 0, v[6:7]
	global_load_dwordx4 v[2:5], v[30:31], off
	global_load_dwordx4 v[6:9], v[30:31], off offset:1024
	global_load_dwordx4 v[26:29], v[30:31], off offset:2048
	global_load_dwordx4 v[50:53], v[30:31], off offset:3072
	v_mbcnt_hi_u32_b32 v23, -1, v227
	v_and_b32_e32 v36, 64, v23
	v_xor_b32_e32 v25, 1, v23
	v_add_u32_e32 v36, 64, v36
	v_cmp_lt_i32_e32 vcc, v25, v36
	s_waitcnt vmcnt(3)
	v_cvt_pk_bf16_f32 v48, v2, v3
	v_cvt_pk_bf16_f32 v49, v4, v5
	global_store_dwordx2 v[34:35], v[48:49], off
	v_pk_mul_f32 v[2:3], v[2:3], v[2:3]
	v_pk_mul_f32 v[4:5], v[4:5], v[4:5]
	v_add_f32_e32 v2, v2, v3
	v_add_f32_e32 v2, v2, v4
	v_add_f32_e32 v37, v2, v5
	v_cndmask_b32_e32 v25, v23, v25, vcc
	v_lshlrev_b32_e32 v25, 2, v25
	s_waitcnt vmcnt(3)
	v_cvt_pk_bf16_f32 v54, v6, v7
	v_cvt_pk_bf16_f32 v55, v8, v9
	global_store_dwordx2 v[34:35], v[54:55], off offset:512
	v_pk_mul_f32 v[2:3], v[6:7], v[6:7]
	v_pk_mul_f32 v[4:5], v[8:9], v[8:9]
	v_add_f32_e32 v2, v2, v3
	v_add_f32_e32 v2, v2, v4
	v_add_f32_e32 v2, v2, v5
	v_add_f32_e32 v6, v37, v2
	s_waitcnt vmcnt(3)
	v_cvt_pk_bf16_f32 v32, v26, v27
	v_cvt_pk_bf16_f32 v33, v28, v29
	global_store_dwordx2 v[34:35], v[32:33], off offset:1024
	v_pk_mul_f32 v[2:3], v[26:27], v[26:27]
	v_pk_mul_f32 v[4:5], v[28:29], v[28:29]
	v_add_f32_e32 v2, v2, v3
	v_add_f32_e32 v2, v2, v4
	v_add_f32_e32 v2, v2, v5
	v_add_f32_e32 v6, v6, v2
	s_waitcnt vmcnt(3)
	v_pk_mul_f32 v[2:3], v[50:51], v[50:51]
	v_pk_mul_f32 v[4:5], v[52:53], v[52:53]
	v_add_f32_e32 v2, v2, v3
	v_add_f32_e32 v2, v2, v4
	v_add_f32_e32 v2, v2, v5
	v_add_f32_e32 v2, v6, v2
	ds_bpermute_b32 v3, v25, v2
	v_xor_b32_e32 v4, 2, v23
	v_cmp_lt_i32_e32 vcc, v4, v36
	v_cvt_pk_bf16_f32 v5, v52, v53
	s_waitcnt lgkmcnt(0)
	v_add_f32_e32 v2, v2, v3
	v_cndmask_b32_e32 v4, v23, v4, vcc
	v_lshlrev_b32_e32 v4, 2, v4
	ds_bpermute_b32 v3, v4, v2
	v_xor_b32_e32 v4, 4, v23
	v_cmp_lt_i32_e32 vcc, v4, v36
	s_waitcnt lgkmcnt(0)
	v_add_f32_e32 v2, v2, v3
	v_cndmask_b32_e32 v4, v23, v4, vcc
	v_lshlrev_b32_e32 v4, 2, v4
	ds_bpermute_b32 v3, v4, v2
	v_xor_b32_e32 v4, 8, v23
	v_cmp_lt_i32_e32 vcc, v4, v36
	s_waitcnt lgkmcnt(0)
	v_add_f32_e32 v2, v2, v3
	v_cndmask_b32_e32 v4, v23, v4, vcc
	v_lshlrev_b32_e32 v4, 2, v4
	ds_bpermute_b32 v3, v4, v2
	v_xor_b32_e32 v4, 16, v23
	v_cmp_lt_i32_e32 vcc, v4, v36
	s_waitcnt lgkmcnt(0)
	v_add_f32_e32 v2, v2, v3
	v_cndmask_b32_e32 v4, v23, v4, vcc
	v_lshlrev_b32_e32 v4, 2, v4
	ds_bpermute_b32 v3, v4, v2
	v_xor_b32_e32 v4, 32, v23
	v_cmp_lt_i32_e32 vcc, v4, v36
	s_waitcnt lgkmcnt(0)
	v_add_f32_e32 v2, v2, v3
	v_cndmask_b32_e32 v4, v23, v4, vcc
	v_lshlrev_b32_e32 v3, 2, v4
	ds_bpermute_b32 v3, v3, v2
	v_cvt_pk_bf16_f32 v4, v50, v51
	global_store_dwordx2 v[34:35], v[4:5], off offset:1536
	s_and_saveexec_b64 s[22:23], s[38:39]
	s_cbranch_execz .LBB0_291
	v_readlane_b32 s0, v249, 8
	v_readlane_b32 s1, v249, 9
	s_waitcnt lgkmcnt(0)
	v_add_f32_e32 v2, v2, v3
	v_lshl_add_u64 v[4:5], v[20:21], 2, s[0:1]
	global_store_dword v[4:5], v2, off

.LBB0_292:
	s_andn2_b64 vcc, exec, s[22:23]
	s_cbranch_vccnz .LBB0_296
	v_add_u32_e32 v2, 0x4000, v20
	s_waitcnt lgkmcnt(0)
	v_ashrrev_i32_e32 v3, 31, v2
	v_lshlrev_b64 v[4:5], 12, v[2:3]
	v_lshl_add_u64 v[8:9], v[14:15], 0, v[4:5]
	v_lshlrev_b64 v[26:27], 11, v[2:3]
	v_lshl_add_u64 v[48:49], v[16:17], 0, v[26:27]
	global_load_dwordx4 v[4:7], v[8:9], off
	global_load_dwordx4 v[26:29], v[8:9], off offset:1024
	global_load_dwordx4 v[30:33], v[8:9], off offset:2048
	global_load_dwordx4 v[34:37], v[8:9], off offset:3072
	s_waitcnt vmcnt(3)
	v_cvt_pk_bf16_f32 v50, v4, v5
	v_cvt_pk_bf16_f32 v51, v6, v7
	global_store_dwordx2 v[48:49], v[50:51], off
	v_pk_mul_f32 v[4:5], v[4:5], v[4:5]
	v_pk_mul_f32 v[6:7], v[6:7], v[6:7]
	v_add_f32_e32 v4, v4, v5
	v_add_f32_e32 v4, v4, v6
	v_add_f32_e32 v23, v4, v7
	s_waitcnt vmcnt(3)
	v_cvt_pk_bf16_f32 v52, v26, v27
	v_cvt_pk_bf16_f32 v53, v28, v29
	global_store_dwordx2 v[48:49], v[52:53], off offset:512
	v_pk_mul_f32 v[4:5], v[26:27], v[26:27]
	v_pk_mul_f32 v[6:7], v[28:29], v[28:29]
	v_add_f32_e32 v4, v4, v5
	v_add_f32_e32 v4, v4, v6
	v_add_f32_e32 v4, v4, v7
	v_add_f32_e32 v23, v23, v4
	s_waitcnt vmcnt(3)
	v_cvt_pk_bf16_f32 v54, v30, v31
	v_cvt_pk_bf16_f32 v55, v32, v33
	global_store_dwordx2 v[48:49], v[54:55], off offset:1024
	v_pk_mul_f32 v[4:5], v[30:31], v[30:31]
	v_pk_mul_f32 v[6:7], v[32:33], v[32:33]
	v_add_f32_e32 v4, v4, v5
	v_add_f32_e32 v4, v4, v6
	v_mbcnt_hi_u32_b32 v8, -1, v227
	v_add_f32_e32 v4, v4, v7
	v_and_b32_e32 v21, 64, v8
	v_add_f32_e32 v23, v23, v4
	v_xor_b32_e32 v9, 1, v8
	v_add_u32_e32 v21, 64, v21
	v_cmp_lt_i32_e32 vcc, v9, v21
	s_waitcnt vmcnt(3)
	v_pk_mul_f32 v[4:5], v[34:35], v[34:35]
	v_pk_mul_f32 v[6:7], v[36:37], v[36:37]
	v_add_f32_e32 v4, v4, v5
	v_add_f32_e32 v4, v4, v6
	v_cndmask_b32_e32 v9, v8, v9, vcc
	v_add_f32_e32 v4, v4, v7
	v_lshlrev_b32_e32 v9, 2, v9
	v_add_f32_e32 v4, v23, v4
	ds_bpermute_b32 v5, v9, v4
	v_xor_b32_e32 v6, 2, v8
	v_cmp_lt_i32_e32 vcc, v6, v21
	v_cvt_pk_bf16_f32 v7, v36, v37
	s_waitcnt lgkmcnt(0)
	v_add_f32_e32 v4, v4, v5
	v_cndmask_b32_e32 v6, v8, v6, vcc
	v_lshlrev_b32_e32 v6, 2, v6
	ds_bpermute_b32 v5, v6, v4
	v_xor_b32_e32 v6, 4, v8
	v_cmp_lt_i32_e32 vcc, v6, v21
	s_waitcnt lgkmcnt(0)
	v_add_f32_e32 v4, v4, v5
	v_cndmask_b32_e32 v6, v8, v6, vcc
	v_lshlrev_b32_e32 v6, 2, v6
	ds_bpermute_b32 v5, v6, v4
	v_xor_b32_e32 v6, 8, v8
	v_cmp_lt_i32_e32 vcc, v6, v21
	s_waitcnt lgkmcnt(0)
	v_add_f32_e32 v4, v4, v5
	v_cndmask_b32_e32 v6, v8, v6, vcc
	v_lshlrev_b32_e32 v6, 2, v6
	ds_bpermute_b32 v5, v6, v4
	v_xor_b32_e32 v6, 16, v8
	v_cmp_lt_i32_e32 vcc, v6, v21
	s_waitcnt lgkmcnt(0)
	v_add_f32_e32 v4, v4, v5
	v_cndmask_b32_e32 v6, v8, v6, vcc
	v_lshlrev_b32_e32 v6, 2, v6
	ds_bpermute_b32 v5, v6, v4
	v_xor_b32_e32 v6, 32, v8
	v_cmp_lt_i32_e32 vcc, v6, v21
	s_waitcnt lgkmcnt(0)
	v_add_f32_e32 v4, v4, v5
	v_cndmask_b32_e32 v6, v8, v6, vcc
	v_lshlrev_b32_e32 v5, 2, v6
	ds_bpermute_b32 v5, v5, v4
	v_cvt_pk_bf16_f32 v6, v34, v35
	global_store_dwordx2 v[48:49], v[6:7], off offset:1536
	s_and_saveexec_b64 s[22:23], s[38:39]
	s_cbranch_execz .LBB0_295
	v_lshl_add_u64 v[2:3], v[2:3], 2, s[24:25]
	s_waitcnt lgkmcnt(0)
	v_add_f32_e32 v4, v4, v5
	global_store_dword v[2:3], v4, off

.LBB0_366:
	s_or_b64 exec, exec, s[28:29]
	v_lshrrev_b32_e32 v5, 6, v21
	v_cvt_f32_u32_e32 v6, v5
	v_sub_u32_e32 v9, 0, v5
	v_sub_u32_e32 v8, 0, v4
	v_max_i32_e32 v8, v4, v8
	v_rcp_iflag_f32_e32 v6, v6
	v_ashrrev_i32_e32 v7, 31, v4
	v_mov_b32_e32 v38, 1.0
	v_mov_b32_e32 v40, 1.0
	v_mul_f32_e32 v6, 0x4f7ffffe, v6
	v_cvt_u32_f32_e32 v6, v6
	v_mul_lo_u32 v9, v9, v6
	v_mul_hi_u32 v9, v6, v9
	v_add_u32_e32 v6, v6, v9
	v_mul_hi_u32 v6, v8, v6
	v_mul_lo_u32 v9, v6, v5
	v_sub_u32_e32 v8, v8, v9
	v_add_u32_e32 v23, 1, v6
	v_sub_u32_e32 v9, v8, v5
	v_cmp_ge_u32_e32 vcc, v8, v5
	s_nop 1
	v_cndmask_b32_e32 v6, v6, v23, vcc
	v_cndmask_b32_e32 v8, v8, v9, vcc
	v_add_u32_e32 v9, 1, v6
	v_cmp_ge_u32_e32 vcc, v8, v5
	v_mov_b32_e32 v23, v0
	s_nop 0
	v_cndmask_b32_e32 v6, v6, v9, vcc
	v_xor_b32_e32 v6, v6, v7
	v_sub_u32_e32 v6, v6, v7
	v_mul_lo_u32 v5, v6, v5
	v_sub_u32_e32 v25, v4, v5
	v_lshlrev_b32_e32 v34, 6, v25
	v_lshlrev_b32_e32 v32, 6, v6
	v_ashrrev_i32_e32 v35, 31, v34
	v_lshl_add_u64 v[2:3], v[34:35], 2, v[2:3]
	v_or_b32_e32 v6, v32, v10
	v_lshl_add_u64 v[36:37], v[2:3], 0, v[22:23]
	v_mad_u64_u32 v[2:3], s[0:1], v6, v21, 0
	v_ashrrev_i32_e32 v7, 31, v6
	v_mov_b32_e32 v4, v3
	v_mad_u64_u32 v[4:5], s[0:1], v7, v21, v[4:5]
	v_mov_b32_e32 v3, v4
	v_lshl_add_u64 v[2:3], v[2:3], 2, v[36:37]
	v_cmp_ne_u64_e32 vcc, 0, v[28:29]
	v_ashrrev_i32_e32 v33, 31, v32
	v_mov_b32_e32 v60, 1.0
	v_mov_b32_e32 v62, 1.0
	s_and_saveexec_b64 s[28:29], vcc
	s_cbranch_execz .Lwc_ng
	v_lshl_add_u64 v[6:7], v[6:7], 2, v[28:29]
	global_load_dword v40, v[6:7], off
	global_load_dword v38, v[6:7], off offset:64
	global_load_dword v60, v[6:7], off offset:128
	global_load_dword v62, v[6:7], off offset:192
.Lwc_ng:
	s_or_b64 exec, exec, s[28:29]
	global_load_dwordx4 v[2:5], v[2:3], off nt
	v_or_b32_e32 v6, v32, v39
	v_mad_u64_u32 v[6:7], s[0:1], v6, v21, 0
	v_mov_b32_e32 v8, v7
	v_mad_u64_u32 v[8:9], s[0:1], v33, v21, v[8:9]
	v_mov_b32_e32 v7, v8
	v_lshl_add_u64 v[6:7], v[6:7], 2, v[36:37]
	global_load_dwordx4 v[6:9], v[6:7], off nt
	v_or_b32_e32 v50, v32, v41
	v_mad_u64_u32 v[50:51], s[0:1], v50, v21, 0
	v_mov_b32_e32 v52, v51
	v_mad_u64_u32 v[52:53], s[0:1], v33, v21, v[52:53]
	v_mov_b32_e32 v51, v52
	v_lshl_add_u64 v[50:51], v[50:51], 2, v[36:37]
	global_load_dwordx4 v[50:53], v[50:51], off nt
	v_or_b32_e32 v54, v32, v42
	v_mad_u64_u32 v[54:55], s[0:1], v54, v21, 0
	v_mov_b32_e32 v56, v55
	v_mad_u64_u32 v[56:57], s[0:1], v33, v21, v[56:57]
	v_mov_b32_e32 v55, v56
	v_lshl_add_u64 v[54:55], v[54:55], 2, v[36:37]
	global_load_dwordx4 v[54:57], v[54:55], off nt
	s_waitcnt vmcnt(3)
	v_pk_mul_f32 v[2:3], v[2:3], v[40:41] op_sel_hi:[1,0]
	ds_write2_b32 v47, v2, v3 offset1:1
	v_pk_mul_f32 v[2:3], v[4:5], v[40:41] op_sel_hi:[1,0]
	ds_write2_b32 v47, v2, v3 offset0:2 offset1:3
	s_waitcnt vmcnt(2)
	v_pk_mul_f32 v[6:7], v[6:7], v[38:39] op_sel_hi:[1,0]
	v_add_u32_e32 v23, 0x1040, v47
	ds_write2_b32 v23, v6, v7 offset1:1
	v_pk_mul_f32 v[6:7], v[8:9], v[38:39] op_sel_hi:[1,0]
	v_add_u32_e32 v8, 0x1048, v47
	ds_write2_b32 v8, v6, v7 offset1:1
	s_waitcnt vmcnt(1)
	v_pk_mul_f32 v[2:3], v[50:51], v[60:61] op_sel_hi:[1,0]
	v_add_u32_e32 v21, 0x2080, v47
	ds_write2_b32 v21, v2, v3 offset1:1
	v_pk_mul_f32 v[2:3], v[52:53], v[60:61] op_sel_hi:[1,0]
	v_add_u32_e32 v4, 0x2088, v47
	ds_write2_b32 v4, v2, v3 offset1:1
	s_waitcnt vmcnt(0)
	v_pk_mul_f32 v[2:3], v[54:55], v[62:63] op_sel_hi:[1,0]
	v_add_u32_e32 v4, 0x30c0, v47
	ds_write2_b32 v4, v2, v3 offset1:1
	v_pk_mul_f32 v[2:3], v[56:57], v[62:63] op_sel_hi:[1,0]
	v_add_u32_e32 v4, 0x30c8, v47
	s_xor_b64 s[0:1], s[40:41], -1
	ds_write2_b32 v4, v2, v3 offset1:1
	v_or_b32_e32 v2, v34, v43
	s_waitcnt lgkmcnt(0)
	s_barrier
	s_and_saveexec_b64 s[28:29], s[0:1]
	s_xor_b64 s[28:29], exec, s[28:29]
	s_cbranch_execz .LBB0_384
	s_and_saveexec_b64 s[40:41], s[34:35]
	s_cbranch_execz .LBB0_383
	s_movk_i32 s0, 0x1ff
	v_cmp_lt_i32_e32 vcc, s0, v2
	s_xor_b64 s[0:1], s[22:23], -1
	s_and_b64 s[0:1], s[0:1], vcc
	s_and_saveexec_b64 s[22:23], s[0:1]
	s_cbranch_execz .LBB0_382
	s_movk_i32 s0, 0x2ff
	v_cmp_lt_u32_e32 vcc, s0, v34
	s_and_saveexec_b64 s[0:1], vcc
	s_xor_b64 s[34:35], exec, s[0:1]
	s_movk_i32 s0, 0x500
	v_add_u32_e32 v3, 0xffffff00, v2
	v_cmp_gt_u32_e32 vcc, s0, v34
	s_nop 1
	v_cndmask_b32_e32 v2, v2, v3, vcc
	s_andn2_saveexec_b64 s[34:35], s[34:35]
	v_add_u32_e32 v2, 0x200, v2
	s_or_b64 exec, exec, s[34:35]
